# pool items: wave-uniform window fast path processing two items per trip (both items loads in flight), on top of rebalance + pre-pass waits
# speedup vs baseline: 1.0110x; 1.0058x over previous
.LBB0_620:
	s_and_b32 s4, s3, 0x1ff
	s_cmp_lt_u32 s4, 2
	s_cbranch_scc1 .Lpool_slow
	s_add_i32 s6, s3, s92
	s_cmp_ge_i32 s6, s98
	s_cbranch_scc1 .Lpool_single
	s_and_b32 s7, s6, 0x1ff
	s_cmp_lt_u32 s7, 2
	s_cbranch_scc1 .Lpool_single
	v_readfirstlane_b32 s4, v178
	v_lshrrev_b32_e32 v96, 8, v178
	v_bfe_u32 v97, v178, 4, 2
	s_lshr_b32 s4, s4, 6
	v_lshl_add_u32 v96, v96, 2, v97
	s_and_b32 s4, s4, 3
	s_lshl_b32 s5, s3, 3
	v_add_u32_e32 v96, s5, v96
	v_and_b32_e32 v97, 15, v178
	s_lshl_b32 s5, s4, 4
	v_add_u32_e32 v97, s5, v97
	v_lshlrev_b32_e32 v97, 4, v97
	v_mov_b32_e32 v99, 0
	v_lshl_add_u32 v98, v96, 10, v97
	v_lshl_add_u64 v[68:69], s[20:21], 0, v[98:99]
	v_lshl_add_u64 v[90:91], s[30:31], 0, v[98:99]
	s_mov_b32 s0, 0xfffff000
	s_mov_b32 s1, -1
	s_lshl_b32 s8, s92, 13
	s_mov_b32 s9, 0
	v_lshl_add_u64 v[216:217], v[68:69], 0, s[8:9]
	v_lshl_add_u64 v[236:237], v[90:91], 0, s[8:9]
	global_load_dwordx4 v[0:3], v[68:69], off
	global_load_dwordx4 v[4:7], v[68:69], off offset:-1024
	s_cmp_eq_u32 s4, 0
	s_cbranch_scc1 .Lpool_ld_pa
	global_load_dwordx4 v[8:11], v[68:69], off offset:-2048
	global_load_dwordx4 v[12:15], v[68:69], off offset:-3072
	s_cmp_eq_u32 s4, 1
	s_cbranch_scc1 .Lpool_ld_pa
	v_lshl_add_u64 v[84:85], v[68:69], 0, s[0:1]
	global_load_dwordx4 v[16:19], v[84:85], off
	global_load_dwordx4 v[20:23], v[84:85], off offset:-1024
	global_load_dwordx4 v[24:27], v[84:85], off offset:-2048
	global_load_dwordx4 v[28:31], v[84:85], off offset:-3072
	s_cmp_eq_u32 s4, 2
	s_cbranch_scc1 .Lpool_ld_pa
	v_lshl_add_u64 v[86:87], v[84:85], 0, s[0:1]
	v_lshl_add_u64 v[88:89], v[86:87], 0, s[0:1]
	global_load_dwordx4 v[32:35], v[86:87], off
	global_load_dwordx4 v[36:39], v[86:87], off offset:-1024
	global_load_dwordx4 v[40:43], v[86:87], off offset:-2048
	global_load_dwordx4 v[44:47], v[86:87], off offset:-3072
	global_load_dwordx4 v[48:51], v[88:89], off
	global_load_dwordx4 v[52:55], v[88:89], off offset:-1024
	global_load_dwordx4 v[56:59], v[88:89], off offset:-2048
	global_load_dwordx4 v[60:63], v[88:89], off offset:-3072
.Lpool_ld_pa:
	global_load_dwordx4 v[100:103], v[216:217], off
	global_load_dwordx4 v[104:107], v[216:217], off offset:-1024
	s_cmp_eq_u32 s4, 0
	s_cbranch_scc1 .Lpool_ld_pb
	global_load_dwordx4 v[108:111], v[216:217], off offset:-2048
	global_load_dwordx4 v[112:115], v[216:217], off offset:-3072
	s_cmp_eq_u32 s4, 1
	s_cbranch_scc1 .Lpool_ld_pb
	v_lshl_add_u64 v[218:219], v[216:217], 0, s[0:1]
	global_load_dwordx4 v[116:119], v[218:219], off
	global_load_dwordx4 v[120:123], v[218:219], off offset:-1024
	global_load_dwordx4 v[124:127], v[218:219], off offset:-2048
	global_load_dwordx4 v[180:183], v[218:219], off offset:-3072
	s_cmp_eq_u32 s4, 2
	s_cbranch_scc1 .Lpool_ld_pb
	v_lshl_add_u64 v[232:233], v[218:219], 0, s[0:1]
	v_lshl_add_u64 v[234:235], v[232:233], 0, s[0:1]
	global_load_dwordx4 v[184:187], v[232:233], off
	global_load_dwordx4 v[188:191], v[232:233], off offset:-1024
	global_load_dwordx4 v[192:195], v[232:233], off offset:-2048
	global_load_dwordx4 v[196:199], v[232:233], off offset:-3072
	global_load_dwordx4 v[200:203], v[234:235], off
	global_load_dwordx4 v[204:207], v[234:235], off offset:-1024
	global_load_dwordx4 v[208:211], v[234:235], off offset:-2048
	global_load_dwordx4 v[212:215], v[234:235], off offset:-3072
.Lpool_ld_pb:
	s_add_i32 s5, s4, 1
	s_lshl_b32 s5, s5, 23
	s_sub_i32 s5, 0x3f800000, s5
	s_waitcnt vmcnt(0)
	v_lshlrev_b32_e32 v74, 16, v0
	v_and_b32_e32 v75, 0xffff0000, v0
	v_lshlrev_b32_e32 v76, 16, v1
	v_and_b32_e32 v77, 0xffff0000, v1
	v_lshlrev_b32_e32 v78, 16, v2
	v_and_b32_e32 v79, 0xffff0000, v2
	v_lshlrev_b32_e32 v80, 16, v3
	v_and_b32_e32 v81, 0xffff0000, v3
	v_pk_add_f32 v[74:75], v[74:75], 0 op_sel_hi:[1,0]
	v_pk_add_f32 v[76:77], v[76:77], 0 op_sel_hi:[1,0]
	v_pk_add_f32 v[78:79], v[78:79], 0 op_sel_hi:[1,0]
	v_pk_add_f32 v[80:81], v[80:81], 0 op_sel_hi:[1,0]
	v_lshlrev_b32_e32 v82, 16, v4
	v_and_b32_e32 v83, 0xffff0000, v4
	v_pk_add_f32 v[74:75], v[74:75], v[82:83]
	v_lshlrev_b32_e32 v82, 16, v5
	v_and_b32_e32 v83, 0xffff0000, v5
	v_pk_add_f32 v[76:77], v[76:77], v[82:83]
	v_lshlrev_b32_e32 v82, 16, v6
	v_and_b32_e32 v83, 0xffff0000, v6
	v_pk_add_f32 v[78:79], v[78:79], v[82:83]
	v_lshlrev_b32_e32 v82, 16, v7
	v_and_b32_e32 v83, 0xffff0000, v7
	v_pk_add_f32 v[80:81], v[80:81], v[82:83]
	s_cmp_eq_u32 s4, 0
	s_cbranch_scc1 .Lpool_acc_pa
	v_lshlrev_b32_e32 v82, 16, v8
	v_and_b32_e32 v83, 0xffff0000, v8
	v_pk_add_f32 v[74:75], v[74:75], v[82:83]
	v_lshlrev_b32_e32 v82, 16, v9
	v_and_b32_e32 v83, 0xffff0000, v9
	v_pk_add_f32 v[76:77], v[76:77], v[82:83]
	v_lshlrev_b32_e32 v82, 16, v10
	v_and_b32_e32 v83, 0xffff0000, v10
	v_pk_add_f32 v[78:79], v[78:79], v[82:83]
	v_lshlrev_b32_e32 v82, 16, v11
	v_and_b32_e32 v83, 0xffff0000, v11
	v_pk_add_f32 v[80:81], v[80:81], v[82:83]
	v_lshlrev_b32_e32 v82, 16, v12
	v_and_b32_e32 v83, 0xffff0000, v12
	v_pk_add_f32 v[74:75], v[74:75], v[82:83]
	v_lshlrev_b32_e32 v82, 16, v13
	v_and_b32_e32 v83, 0xffff0000, v13
	v_pk_add_f32 v[76:77], v[76:77], v[82:83]
	v_lshlrev_b32_e32 v82, 16, v14
	v_and_b32_e32 v83, 0xffff0000, v14
	v_pk_add_f32 v[78:79], v[78:79], v[82:83]
	v_lshlrev_b32_e32 v82, 16, v15
	v_and_b32_e32 v83, 0xffff0000, v15
	v_pk_add_f32 v[80:81], v[80:81], v[82:83]
	s_cmp_eq_u32 s4, 1
	s_cbranch_scc1 .Lpool_acc_pa
	v_lshlrev_b32_e32 v82, 16, v16
	v_and_b32_e32 v83, 0xffff0000, v16
	v_pk_add_f32 v[74:75], v[74:75], v[82:83]
	v_lshlrev_b32_e32 v82, 16, v17
	v_and_b32_e32 v83, 0xffff0000, v17
	v_pk_add_f32 v[76:77], v[76:77], v[82:83]
	v_lshlrev_b32_e32 v82, 16, v18
	v_and_b32_e32 v83, 0xffff0000, v18
	v_pk_add_f32 v[78:79], v[78:79], v[82:83]
	v_lshlrev_b32_e32 v82, 16, v19
	v_and_b32_e32 v83, 0xffff0000, v19
	v_pk_add_f32 v[80:81], v[80:81], v[82:83]
	v_lshlrev_b32_e32 v82, 16, v20
	v_and_b32_e32 v83, 0xffff0000, v20
	v_pk_add_f32 v[74:75], v[74:75], v[82:83]
	v_lshlrev_b32_e32 v82, 16, v21
	v_and_b32_e32 v83, 0xffff0000, v21
	v_pk_add_f32 v[76:77], v[76:77], v[82:83]
	v_lshlrev_b32_e32 v82, 16, v22
	v_and_b32_e32 v83, 0xffff0000, v22
	v_pk_add_f32 v[78:79], v[78:79], v[82:83]
	v_lshlrev_b32_e32 v82, 16, v23
	v_and_b32_e32 v83, 0xffff0000, v23
	v_pk_add_f32 v[80:81], v[80:81], v[82:83]
	v_lshlrev_b32_e32 v82, 16, v24
	v_and_b32_e32 v83, 0xffff0000, v24
	v_pk_add_f32 v[74:75], v[74:75], v[82:83]
	v_lshlrev_b32_e32 v82, 16, v25
	v_and_b32_e32 v83, 0xffff0000, v25
	v_pk_add_f32 v[76:77], v[76:77], v[82:83]
	v_lshlrev_b32_e32 v82, 16, v26
	v_and_b32_e32 v83, 0xffff0000, v26
	v_pk_add_f32 v[78:79], v[78:79], v[82:83]
	v_lshlrev_b32_e32 v82, 16, v27
	v_and_b32_e32 v83, 0xffff0000, v27
	v_pk_add_f32 v[80:81], v[80:81], v[82:83]
	v_lshlrev_b32_e32 v82, 16, v28
	v_and_b32_e32 v83, 0xffff0000, v28
	v_pk_add_f32 v[74:75], v[74:75], v[82:83]
	v_lshlrev_b32_e32 v82, 16, v29
	v_and_b32_e32 v83, 0xffff0000, v29
	v_pk_add_f32 v[76:77], v[76:77], v[82:83]
	v_lshlrev_b32_e32 v82, 16, v30
	v_and_b32_e32 v83, 0xffff0000, v30
	v_pk_add_f32 v[78:79], v[78:79], v[82:83]
	v_lshlrev_b32_e32 v82, 16, v31
	v_and_b32_e32 v83, 0xffff0000, v31
	v_pk_add_f32 v[80:81], v[80:81], v[82:83]
	s_cmp_eq_u32 s4, 2
	s_cbranch_scc1 .Lpool_acc_pa
	v_lshlrev_b32_e32 v82, 16, v32
	v_and_b32_e32 v83, 0xffff0000, v32
	v_pk_add_f32 v[74:75], v[74:75], v[82:83]
	v_lshlrev_b32_e32 v82, 16, v33
	v_and_b32_e32 v83, 0xffff0000, v33
	v_pk_add_f32 v[76:77], v[76:77], v[82:83]
	v_lshlrev_b32_e32 v82, 16, v34
	v_and_b32_e32 v83, 0xffff0000, v34
	v_pk_add_f32 v[78:79], v[78:79], v[82:83]
	v_lshlrev_b32_e32 v82, 16, v35
	v_and_b32_e32 v83, 0xffff0000, v35
	v_pk_add_f32 v[80:81], v[80:81], v[82:83]
	v_lshlrev_b32_e32 v82, 16, v36
	v_and_b32_e32 v83, 0xffff0000, v36
	v_pk_add_f32 v[74:75], v[74:75], v[82:83]
	v_lshlrev_b32_e32 v82, 16, v37
	v_and_b32_e32 v83, 0xffff0000, v37
	v_pk_add_f32 v[76:77], v[76:77], v[82:83]
	v_lshlrev_b32_e32 v82, 16, v38
	v_and_b32_e32 v83, 0xffff0000, v38
	v_pk_add_f32 v[78:79], v[78:79], v[82:83]
	v_lshlrev_b32_e32 v82, 16, v39
	v_and_b32_e32 v83, 0xffff0000, v39
	v_pk_add_f32 v[80:81], v[80:81], v[82:83]
	v_lshlrev_b32_e32 v82, 16, v40
	v_and_b32_e32 v83, 0xffff0000, v40
	v_pk_add_f32 v[74:75], v[74:75], v[82:83]
	v_lshlrev_b32_e32 v82, 16, v41
	v_and_b32_e32 v83, 0xffff0000, v41
	v_pk_add_f32 v[76:77], v[76:77], v[82:83]
	v_lshlrev_b32_e32 v82, 16, v42
	v_and_b32_e32 v83, 0xffff0000, v42
	v_pk_add_f32 v[78:79], v[78:79], v[82:83]
	v_lshlrev_b32_e32 v82, 16, v43
	v_and_b32_e32 v83, 0xffff0000, v43
	v_pk_add_f32 v[80:81], v[80:81], v[82:83]
	v_lshlrev_b32_e32 v82, 16, v44
	v_and_b32_e32 v83, 0xffff0000, v44
	v_pk_add_f32 v[74:75], v[74:75], v[82:83]
	v_lshlrev_b32_e32 v82, 16, v45
	v_and_b32_e32 v83, 0xffff0000, v45
	v_pk_add_f32 v[76:77], v[76:77], v[82:83]
	v_lshlrev_b32_e32 v82, 16, v46
	v_and_b32_e32 v83, 0xffff0000, v46
	v_pk_add_f32 v[78:79], v[78:79], v[82:83]
	v_lshlrev_b32_e32 v82, 16, v47
	v_and_b32_e32 v83, 0xffff0000, v47
	v_pk_add_f32 v[80:81], v[80:81], v[82:83]
	v_lshlrev_b32_e32 v82, 16, v48
	v_and_b32_e32 v83, 0xffff0000, v48
	v_pk_add_f32 v[74:75], v[74:75], v[82:83]
	v_lshlrev_b32_e32 v82, 16, v49
	v_and_b32_e32 v83, 0xffff0000, v49
	v_pk_add_f32 v[76:77], v[76:77], v[82:83]
	v_lshlrev_b32_e32 v82, 16, v50
	v_and_b32_e32 v83, 0xffff0000, v50
	v_pk_add_f32 v[78:79], v[78:79], v[82:83]
	v_lshlrev_b32_e32 v82, 16, v51
	v_and_b32_e32 v83, 0xffff0000, v51
	v_pk_add_f32 v[80:81], v[80:81], v[82:83]
	v_lshlrev_b32_e32 v82, 16, v52
	v_and_b32_e32 v83, 0xffff0000, v52
	v_pk_add_f32 v[74:75], v[74:75], v[82:83]
	v_lshlrev_b32_e32 v82, 16, v53
	v_and_b32_e32 v83, 0xffff0000, v53
	v_pk_add_f32 v[76:77], v[76:77], v[82:83]
	v_lshlrev_b32_e32 v82, 16, v54
	v_and_b32_e32 v83, 0xffff0000, v54
	v_pk_add_f32 v[78:79], v[78:79], v[82:83]
	v_lshlrev_b32_e32 v82, 16, v55
	v_and_b32_e32 v83, 0xffff0000, v55
	v_pk_add_f32 v[80:81], v[80:81], v[82:83]
	v_lshlrev_b32_e32 v82, 16, v56
	v_and_b32_e32 v83, 0xffff0000, v56
	v_pk_add_f32 v[74:75], v[74:75], v[82:83]
	v_lshlrev_b32_e32 v82, 16, v57
	v_and_b32_e32 v83, 0xffff0000, v57
	v_pk_add_f32 v[76:77], v[76:77], v[82:83]
	v_lshlrev_b32_e32 v82, 16, v58
	v_and_b32_e32 v83, 0xffff0000, v58
	v_pk_add_f32 v[78:79], v[78:79], v[82:83]
	v_lshlrev_b32_e32 v82, 16, v59
	v_and_b32_e32 v83, 0xffff0000, v59
	v_pk_add_f32 v[80:81], v[80:81], v[82:83]
	v_lshlrev_b32_e32 v82, 16, v60
	v_and_b32_e32 v83, 0xffff0000, v60
	v_pk_add_f32 v[74:75], v[74:75], v[82:83]
	v_lshlrev_b32_e32 v82, 16, v61
	v_and_b32_e32 v83, 0xffff0000, v61
	v_pk_add_f32 v[76:77], v[76:77], v[82:83]
	v_lshlrev_b32_e32 v82, 16, v62
	v_and_b32_e32 v83, 0xffff0000, v62
	v_pk_add_f32 v[78:79], v[78:79], v[82:83]
	v_lshlrev_b32_e32 v82, 16, v63
	v_and_b32_e32 v83, 0xffff0000, v63
	v_pk_add_f32 v[80:81], v[80:81], v[82:83]
.Lpool_acc_pa:
	v_lshlrev_b32_e32 v82, 16, v0
	v_and_b32_e32 v83, 0xffff0000, v0
	v_fma_f32 v74, v74, s5, -v82
	v_fma_f32 v75, v75, s5, -v83
	v_cvt_pk_bf16_f32 v92, v74, v75
	v_lshlrev_b32_e32 v82, 16, v1
	v_and_b32_e32 v83, 0xffff0000, v1
	v_fma_f32 v76, v76, s5, -v82
	v_fma_f32 v77, v77, s5, -v83
	v_cvt_pk_bf16_f32 v93, v76, v77
	v_lshlrev_b32_e32 v82, 16, v2
	v_and_b32_e32 v83, 0xffff0000, v2
	v_fma_f32 v78, v78, s5, -v82
	v_fma_f32 v79, v79, s5, -v83
	v_cvt_pk_bf16_f32 v94, v78, v79
	v_lshlrev_b32_e32 v82, 16, v3
	v_and_b32_e32 v83, 0xffff0000, v3
	v_fma_f32 v80, v80, s5, -v82
	v_fma_f32 v81, v81, s5, -v83
	v_cvt_pk_bf16_f32 v95, v80, v81
	global_store_dwordx4 v[90:91], v[92:95], off
	v_lshlrev_b32_e32 v74, 16, v100
	v_and_b32_e32 v75, 0xffff0000, v100
	v_lshlrev_b32_e32 v76, 16, v101
	v_and_b32_e32 v77, 0xffff0000, v101
	v_lshlrev_b32_e32 v78, 16, v102
	v_and_b32_e32 v79, 0xffff0000, v102
	v_lshlrev_b32_e32 v80, 16, v103
	v_and_b32_e32 v81, 0xffff0000, v103
	v_pk_add_f32 v[74:75], v[74:75], 0 op_sel_hi:[1,0]
	v_pk_add_f32 v[76:77], v[76:77], 0 op_sel_hi:[1,0]
	v_pk_add_f32 v[78:79], v[78:79], 0 op_sel_hi:[1,0]
	v_pk_add_f32 v[80:81], v[80:81], 0 op_sel_hi:[1,0]
	v_lshlrev_b32_e32 v82, 16, v104
	v_and_b32_e32 v83, 0xffff0000, v104
	v_pk_add_f32 v[74:75], v[74:75], v[82:83]
	v_lshlrev_b32_e32 v82, 16, v105
	v_and_b32_e32 v83, 0xffff0000, v105
	v_pk_add_f32 v[76:77], v[76:77], v[82:83]
	v_lshlrev_b32_e32 v82, 16, v106
	v_and_b32_e32 v83, 0xffff0000, v106
	v_pk_add_f32 v[78:79], v[78:79], v[82:83]
	v_lshlrev_b32_e32 v82, 16, v107
	v_and_b32_e32 v83, 0xffff0000, v107
	v_pk_add_f32 v[80:81], v[80:81], v[82:83]
	s_cmp_eq_u32 s4, 0
	s_cbranch_scc1 .Lpool_acc_pb
	v_lshlrev_b32_e32 v82, 16, v108
	v_and_b32_e32 v83, 0xffff0000, v108
	v_pk_add_f32 v[74:75], v[74:75], v[82:83]
	v_lshlrev_b32_e32 v82, 16, v109
	v_and_b32_e32 v83, 0xffff0000, v109
	v_pk_add_f32 v[76:77], v[76:77], v[82:83]
	v_lshlrev_b32_e32 v82, 16, v110
	v_and_b32_e32 v83, 0xffff0000, v110
	v_pk_add_f32 v[78:79], v[78:79], v[82:83]
	v_lshlrev_b32_e32 v82, 16, v111
	v_and_b32_e32 v83, 0xffff0000, v111
	v_pk_add_f32 v[80:81], v[80:81], v[82:83]
	v_lshlrev_b32_e32 v82, 16, v112
	v_and_b32_e32 v83, 0xffff0000, v112
	v_pk_add_f32 v[74:75], v[74:75], v[82:83]
	v_lshlrev_b32_e32 v82, 16, v113
	v_and_b32_e32 v83, 0xffff0000, v113
	v_pk_add_f32 v[76:77], v[76:77], v[82:83]
	v_lshlrev_b32_e32 v82, 16, v114
	v_and_b32_e32 v83, 0xffff0000, v114
	v_pk_add_f32 v[78:79], v[78:79], v[82:83]
	v_lshlrev_b32_e32 v82, 16, v115
	v_and_b32_e32 v83, 0xffff0000, v115
	v_pk_add_f32 v[80:81], v[80:81], v[82:83]
	s_cmp_eq_u32 s4, 1
	s_cbranch_scc1 .Lpool_acc_pb
	v_lshlrev_b32_e32 v82, 16, v116
	v_and_b32_e32 v83, 0xffff0000, v116
	v_pk_add_f32 v[74:75], v[74:75], v[82:83]
	v_lshlrev_b32_e32 v82, 16, v117
	v_and_b32_e32 v83, 0xffff0000, v117
	v_pk_add_f32 v[76:77], v[76:77], v[82:83]
	v_lshlrev_b32_e32 v82, 16, v118
	v_and_b32_e32 v83, 0xffff0000, v118
	v_pk_add_f32 v[78:79], v[78:79], v[82:83]
	v_lshlrev_b32_e32 v82, 16, v119
	v_and_b32_e32 v83, 0xffff0000, v119
	v_pk_add_f32 v[80:81], v[80:81], v[82:83]
	v_lshlrev_b32_e32 v82, 16, v120
	v_and_b32_e32 v83, 0xffff0000, v120
	v_pk_add_f32 v[74:75], v[74:75], v[82:83]
	v_lshlrev_b32_e32 v82, 16, v121
	v_and_b32_e32 v83, 0xffff0000, v121
	v_pk_add_f32 v[76:77], v[76:77], v[82:83]
	v_lshlrev_b32_e32 v82, 16, v122
	v_and_b32_e32 v83, 0xffff0000, v122
	v_pk_add_f32 v[78:79], v[78:79], v[82:83]
	v_lshlrev_b32_e32 v82, 16, v123
	v_and_b32_e32 v83, 0xffff0000, v123
	v_pk_add_f32 v[80:81], v[80:81], v[82:83]
	v_lshlrev_b32_e32 v82, 16, v124
	v_and_b32_e32 v83, 0xffff0000, v124
	v_pk_add_f32 v[74:75], v[74:75], v[82:83]
	v_lshlrev_b32_e32 v82, 16, v125
	v_and_b32_e32 v83, 0xffff0000, v125
	v_pk_add_f32 v[76:77], v[76:77], v[82:83]
	v_lshlrev_b32_e32 v82, 16, v126
	v_and_b32_e32 v83, 0xffff0000, v126
	v_pk_add_f32 v[78:79], v[78:79], v[82:83]
	v_lshlrev_b32_e32 v82, 16, v127
	v_and_b32_e32 v83, 0xffff0000, v127
	v_pk_add_f32 v[80:81], v[80:81], v[82:83]
	v_lshlrev_b32_e32 v82, 16, v180
	v_and_b32_e32 v83, 0xffff0000, v180
	v_pk_add_f32 v[74:75], v[74:75], v[82:83]
	v_lshlrev_b32_e32 v82, 16, v181
	v_and_b32_e32 v83, 0xffff0000, v181
	v_pk_add_f32 v[76:77], v[76:77], v[82:83]
	v_lshlrev_b32_e32 v82, 16, v182
	v_and_b32_e32 v83, 0xffff0000, v182
	v_pk_add_f32 v[78:79], v[78:79], v[82:83]
	v_lshlrev_b32_e32 v82, 16, v183
	v_and_b32_e32 v83, 0xffff0000, v183
	v_pk_add_f32 v[80:81], v[80:81], v[82:83]
	s_cmp_eq_u32 s4, 2
	s_cbranch_scc1 .Lpool_acc_pb
	v_lshlrev_b32_e32 v82, 16, v184
	v_and_b32_e32 v83, 0xffff0000, v184
	v_pk_add_f32 v[74:75], v[74:75], v[82:83]
	v_lshlrev_b32_e32 v82, 16, v185
	v_and_b32_e32 v83, 0xffff0000, v185
	v_pk_add_f32 v[76:77], v[76:77], v[82:83]
	v_lshlrev_b32_e32 v82, 16, v186
	v_and_b32_e32 v83, 0xffff0000, v186
	v_pk_add_f32 v[78:79], v[78:79], v[82:83]
	v_lshlrev_b32_e32 v82, 16, v187
	v_and_b32_e32 v83, 0xffff0000, v187
	v_pk_add_f32 v[80:81], v[80:81], v[82:83]
	v_lshlrev_b32_e32 v82, 16, v188
	v_and_b32_e32 v83, 0xffff0000, v188
	v_pk_add_f32 v[74:75], v[74:75], v[82:83]
	v_lshlrev_b32_e32 v82, 16, v189
	v_and_b32_e32 v83, 0xffff0000, v189
	v_pk_add_f32 v[76:77], v[76:77], v[82:83]
	v_lshlrev_b32_e32 v82, 16, v190
	v_and_b32_e32 v83, 0xffff0000, v190
	v_pk_add_f32 v[78:79], v[78:79], v[82:83]
	v_lshlrev_b32_e32 v82, 16, v191
	v_and_b32_e32 v83, 0xffff0000, v191
	v_pk_add_f32 v[80:81], v[80:81], v[82:83]
	v_lshlrev_b32_e32 v82, 16, v192
	v_and_b32_e32 v83, 0xffff0000, v192
	v_pk_add_f32 v[74:75], v[74:75], v[82:83]
	v_lshlrev_b32_e32 v82, 16, v193
	v_and_b32_e32 v83, 0xffff0000, v193
	v_pk_add_f32 v[76:77], v[76:77], v[82:83]
	v_lshlrev_b32_e32 v82, 16, v194
	v_and_b32_e32 v83, 0xffff0000, v194
	v_pk_add_f32 v[78:79], v[78:79], v[82:83]
	v_lshlrev_b32_e32 v82, 16, v195
	v_and_b32_e32 v83, 0xffff0000, v195
	v_pk_add_f32 v[80:81], v[80:81], v[82:83]
	v_lshlrev_b32_e32 v82, 16, v196
	v_and_b32_e32 v83, 0xffff0000, v196
	v_pk_add_f32 v[74:75], v[74:75], v[82:83]
	v_lshlrev_b32_e32 v82, 16, v197
	v_and_b32_e32 v83, 0xffff0000, v197
	v_pk_add_f32 v[76:77], v[76:77], v[82:83]
	v_lshlrev_b32_e32 v82, 16, v198
	v_and_b32_e32 v83, 0xffff0000, v198
	v_pk_add_f32 v[78:79], v[78:79], v[82:83]
	v_lshlrev_b32_e32 v82, 16, v199
	v_and_b32_e32 v83, 0xffff0000, v199
	v_pk_add_f32 v[80:81], v[80:81], v[82:83]
	v_lshlrev_b32_e32 v82, 16, v200
	v_and_b32_e32 v83, 0xffff0000, v200
	v_pk_add_f32 v[74:75], v[74:75], v[82:83]
	v_lshlrev_b32_e32 v82, 16, v201
	v_and_b32_e32 v83, 0xffff0000, v201
	v_pk_add_f32 v[76:77], v[76:77], v[82:83]
	v_lshlrev_b32_e32 v82, 16, v202
	v_and_b32_e32 v83, 0xffff0000, v202
	v_pk_add_f32 v[78:79], v[78:79], v[82:83]
	v_lshlrev_b32_e32 v82, 16, v203
	v_and_b32_e32 v83, 0xffff0000, v203
	v_pk_add_f32 v[80:81], v[80:81], v[82:83]
	v_lshlrev_b32_e32 v82, 16, v204
	v_and_b32_e32 v83, 0xffff0000, v204
	v_pk_add_f32 v[74:75], v[74:75], v[82:83]
	v_lshlrev_b32_e32 v82, 16, v205
	v_and_b32_e32 v83, 0xffff0000, v205
	v_pk_add_f32 v[76:77], v[76:77], v[82:83]
	v_lshlrev_b32_e32 v82, 16, v206
	v_and_b32_e32 v83, 0xffff0000, v206
	v_pk_add_f32 v[78:79], v[78:79], v[82:83]
	v_lshlrev_b32_e32 v82, 16, v207
	v_and_b32_e32 v83, 0xffff0000, v207
	v_pk_add_f32 v[80:81], v[80:81], v[82:83]
	v_lshlrev_b32_e32 v82, 16, v208
	v_and_b32_e32 v83, 0xffff0000, v208
	v_pk_add_f32 v[74:75], v[74:75], v[82:83]
	v_lshlrev_b32_e32 v82, 16, v209
	v_and_b32_e32 v83, 0xffff0000, v209
	v_pk_add_f32 v[76:77], v[76:77], v[82:83]
	v_lshlrev_b32_e32 v82, 16, v210
	v_and_b32_e32 v83, 0xffff0000, v210
	v_pk_add_f32 v[78:79], v[78:79], v[82:83]
	v_lshlrev_b32_e32 v82, 16, v211
	v_and_b32_e32 v83, 0xffff0000, v211
	v_pk_add_f32 v[80:81], v[80:81], v[82:83]
	v_lshlrev_b32_e32 v82, 16, v212
	v_and_b32_e32 v83, 0xffff0000, v212
	v_pk_add_f32 v[74:75], v[74:75], v[82:83]
	v_lshlrev_b32_e32 v82, 16, v213
	v_and_b32_e32 v83, 0xffff0000, v213
	v_pk_add_f32 v[76:77], v[76:77], v[82:83]
	v_lshlrev_b32_e32 v82, 16, v214
	v_and_b32_e32 v83, 0xffff0000, v214
	v_pk_add_f32 v[78:79], v[78:79], v[82:83]
	v_lshlrev_b32_e32 v82, 16, v215
	v_and_b32_e32 v83, 0xffff0000, v215
	v_pk_add_f32 v[80:81], v[80:81], v[82:83]
.Lpool_acc_pb:
	v_lshlrev_b32_e32 v82, 16, v100
	v_and_b32_e32 v83, 0xffff0000, v100
	v_fma_f32 v74, v74, s5, -v82
	v_fma_f32 v75, v75, s5, -v83
	v_cvt_pk_bf16_f32 v92, v74, v75
	v_lshlrev_b32_e32 v82, 16, v101
	v_and_b32_e32 v83, 0xffff0000, v101
	v_fma_f32 v76, v76, s5, -v82
	v_fma_f32 v77, v77, s5, -v83
	v_cvt_pk_bf16_f32 v93, v76, v77
	v_lshlrev_b32_e32 v82, 16, v102
	v_and_b32_e32 v83, 0xffff0000, v102
	v_fma_f32 v78, v78, s5, -v82
	v_fma_f32 v79, v79, s5, -v83
	v_cvt_pk_bf16_f32 v94, v78, v79
	v_lshlrev_b32_e32 v82, 16, v103
	v_and_b32_e32 v83, 0xffff0000, v103
	v_fma_f32 v80, v80, s5, -v82
	v_fma_f32 v81, v81, s5, -v83
	v_cvt_pk_bf16_f32 v95, v80, v81
	global_store_dwordx4 v[236:237], v[92:95], off
	s_add_i32 s3, s6, s92
	v_add_u32_e32 v73, s2, v73
	v_add_u32_e32 v73, s2, v73
	s_cmp_ge_i32 s3, s98
	s_cbranch_scc1 .LBB0_650
	s_branch .LBB0_620
.Lpool_single:
	v_readfirstlane_b32 s4, v178
	v_lshrrev_b32_e32 v96, 8, v178
	v_bfe_u32 v97, v178, 4, 2
	s_lshr_b32 s4, s4, 6
	v_lshl_add_u32 v96, v96, 2, v97
	s_and_b32 s4, s4, 3
	s_lshl_b32 s5, s3, 3
	v_add_u32_e32 v96, s5, v96
	v_and_b32_e32 v97, 15, v178
	s_lshl_b32 s5, s4, 4
	v_add_u32_e32 v97, s5, v97
	v_lshlrev_b32_e32 v97, 4, v97
	v_mov_b32_e32 v99, 0
	v_lshl_add_u32 v98, v96, 10, v97
	v_lshl_add_u64 v[68:69], s[20:21], 0, v[98:99]
	v_lshl_add_u64 v[90:91], s[30:31], 0, v[98:99]
	s_mov_b32 s0, 0xfffff000
	s_mov_b32 s1, -1
	global_load_dwordx4 v[0:3], v[68:69], off
	global_load_dwordx4 v[4:7], v[68:69], off offset:-1024
	s_cmp_eq_u32 s4, 0
	s_cbranch_scc1 .Lpool_ld_sa
	global_load_dwordx4 v[8:11], v[68:69], off offset:-2048
	global_load_dwordx4 v[12:15], v[68:69], off offset:-3072
	s_cmp_eq_u32 s4, 1
	s_cbranch_scc1 .Lpool_ld_sa
	v_lshl_add_u64 v[84:85], v[68:69], 0, s[0:1]
	global_load_dwordx4 v[16:19], v[84:85], off
	global_load_dwordx4 v[20:23], v[84:85], off offset:-1024
	global_load_dwordx4 v[24:27], v[84:85], off offset:-2048
	global_load_dwordx4 v[28:31], v[84:85], off offset:-3072
	s_cmp_eq_u32 s4, 2
	s_cbranch_scc1 .Lpool_ld_sa
	v_lshl_add_u64 v[86:87], v[84:85], 0, s[0:1]
	v_lshl_add_u64 v[88:89], v[86:87], 0, s[0:1]
	global_load_dwordx4 v[32:35], v[86:87], off
	global_load_dwordx4 v[36:39], v[86:87], off offset:-1024
	global_load_dwordx4 v[40:43], v[86:87], off offset:-2048
	global_load_dwordx4 v[44:47], v[86:87], off offset:-3072
	global_load_dwordx4 v[48:51], v[88:89], off
	global_load_dwordx4 v[52:55], v[88:89], off offset:-1024
	global_load_dwordx4 v[56:59], v[88:89], off offset:-2048
	global_load_dwordx4 v[60:63], v[88:89], off offset:-3072

.Lpool_acc_sa:
	v_lshlrev_b32_e32 v82, 16, v0
	v_and_b32_e32 v83, 0xffff0000, v0
	v_fma_f32 v74, v74, s5, -v82
	v_fma_f32 v75, v75, s5, -v83
	v_cvt_pk_bf16_f32 v92, v74, v75
	v_lshlrev_b32_e32 v82, 16, v1
	v_and_b32_e32 v83, 0xffff0000, v1
	v_fma_f32 v76, v76, s5, -v82
	v_fma_f32 v77, v77, s5, -v83
	v_cvt_pk_bf16_f32 v93, v76, v77
	v_lshlrev_b32_e32 v82, 16, v2
	v_and_b32_e32 v83, 0xffff0000, v2
	v_fma_f32 v78, v78, s5, -v82
	v_fma_f32 v79, v79, s5, -v83
	v_cvt_pk_bf16_f32 v94, v78, v79
	v_lshlrev_b32_e32 v82, 16, v3
	v_and_b32_e32 v83, 0xffff0000, v3
	v_fma_f32 v80, v80, s5, -v82
	v_fma_f32 v81, v81, s5, -v83
	v_cvt_pk_bf16_f32 v95, v80, v81
	global_store_dwordx4 v[90:91], v[92:95], off
	s_add_i32 s3, s3, s92
	v_add_u32_e32 v73, s2, v73
	s_cmp_ge_i32 s3, s98
	s_cbranch_scc1 .LBB0_650
	s_branch .LBB0_620
